# NSA compressed pass2: batch all 8 K ds_reads ahead of the QK MFMAs (order-preserving, counted lgkmcnt)
# baseline (speedup 1.0000x reference)
; #define MFMA32(a, b, c) __builtin_amdgcn_mfma_f32_32x32x16_bf16((a), (b), (c), 0, 0, 0)
; DI float fexp2(float x) { return __builtin_amdgcn_exp2f(x); }
; DI void qk_tile(const u16* Ks, const bf16x8* qf, f32x16* s, int rl, int hh) {
; #pragma unroll
;   for (int kb = 0; kb < 2; ++kb) {
; #pragma unroll
;     for (int i = 0; i < 16; ++i) s[kb][i] = 0.f;
; #pragma unroll
;     for (int ks = 0; ks < 4; ++ks) {
;       bf16x8 a = *(const bf16x8*)(Ks + (kb * 32 + rl) * KVS + ks * 16 + hh * 8);
;       s[kb] = MFMA32(a, qf[ks], s[kb]);
;     }
;   }
; }
; DI void pv_tile(const u16* Vs, const f32x16* s, f32x16* o, int rl, int hh) {
; #pragma unroll
;   for (int kk = 0; kk < 4; ++kk) {
;     const int kb = kk >> 1, i0 = 8 * (kk & 1);
;     bf16x8 pf = pack8(s[kb][i0], s[kb][i0 + 1], s[kb][i0 + 2], s[kb][i0 + 3], s[kb][i0 + 4], s[kb][i0 + 5], s[kb][i0 + 6], s[kb][i0 + 7]);
; #pragma unroll
;     for (int db = 0; db < 2; ++db) {
;       const u16* vp = Vs + (db * 32 + rl) * KVS + kk * 16 + hh * 4;
;       s16x4 lo = *(const s16x4*)vp, hi = *(const s16x4*)(vp + 8);
;       bf16x8 a = __builtin_shufflevector(lo, hi, 0, 1, 2, 3, 4, 5, 6, 7);
;       o[db] = MFMA32(a, pf, o[db]);
;     }
;   }
; }
; DI void nsa_item(int ws, PP p, char* shm, int item) {
;     ...
;     auto body2 = [&](int i, const u16* Ks, const u16* Vs) {
;       const uint32_t vm = range_mask(i * 64, 0, cmax, hh);
;       f32x16 s[2];
;       qk_tile(Ks, qn, s, rl, hh);
; #pragma unroll
;       for (int kb = 0; kb < 2; ++kb)
; #pragma unroll
;         for (int ii = 0; ii < 16; ++ii) s[kb][ii] = ((vm >> (kb * 16 + ii)) & 1u) ? fexp2(__builtin_fmaf(s[kb][ii], SCL2, -m)) * invl : 0.f;
;       pv_tile(Vs, s, o, rl, hh);
.LBB0_1610:
	s_or_b64 exec, exec, s[14:15]
	s_and_b32 s16, s18, 1
	s_mul_i32 s14, s16, 0x4800
	v_or_b32_e32 v13, s14, v0
	v_lshl_add_u32 v125, v246, 1, v13
	ds_read_b128 v[148:151], v125
	ds_read_b128 v[152:155], v125 offset:32
	ds_read_b128 v[156:159], v125 offset:64
	ds_read_b128 v[126:129], v125 offset:96
	ds_read_b128 v[160:163], v125 offset:4608
	ds_read_b128 v[130:133], v125 offset:4640
	ds_read_b128 v[134:137], v125 offset:4672
	ds_read_b128 v[138:141], v125 offset:4704
	v_and_b32_e32 v13, 1, v12
	v_and_b32_e32 v14, 2, v12
	v_cmp_eq_u32_e32 vcc, 1, v13
	s_waitcnt lgkmcnt(7)
	v_mfma_f32_32x32x16_bf16 v[64:79], v[148:151], v[80:83], 0
	v_and_b32_e32 v15, 4, v12
	v_and_b32_e32 v142, 8, v12
	v_and_b32_e32 v143, 16, v12
	s_waitcnt lgkmcnt(6)
	v_mfma_f32_32x32x16_bf16 v[64:79], v[152:155], v[176:179], v[64:79]
	s_waitcnt lgkmcnt(5)
	v_mfma_f32_32x32x16_bf16 v[64:79], v[156:159], v[180:183], v[64:79]
	s_waitcnt lgkmcnt(4)
	v_mfma_f32_32x32x16_bf16 v[64:79], v[126:129], v[184:187], v[64:79]
	s_waitcnt lgkmcnt(3)
	v_mfma_f32_32x32x16_bf16 v[48:63], v[160:163], v[80:83], 0
	s_nop 9
	v_fma_f32 v64, v64, s9, -v124
	v_fma_f32 v65, v65, s9, -v124
	v_exp_f32_e32 v64, v64
	v_fma_f32 v66, v66, s9, -v124
	v_exp_f32_e32 v65, v65
	v_fma_f32 v67, v67, s9, -v124
	v_exp_f32_e32 v66, v66
	v_fma_f32 v68, v68, s9, -v124
	v_exp_f32_e32 v67, v67
	v_fma_f32 v69, v69, s9, -v124
	v_exp_f32_e32 v68, v68
	v_mul_f32_e32 v64, v11, v64
	v_fma_f32 v70, v70, s9, -v124
	v_exp_f32_e32 v69, v69
	v_mul_f32_e32 v65, v11, v65
	v_cndmask_b32_e32 v144, 0, v64, vcc
	v_cmp_ne_u32_e32 vcc, 0, v14
	v_mul_f32_e32 v66, v11, v66
	s_waitcnt lgkmcnt(2)
	v_mfma_f32_32x32x16_bf16 v[48:63], v[130:133], v[176:179], v[48:63]
	v_cndmask_b32_e32 v145, 0, v65, vcc
	v_cmp_ne_u32_e32 vcc, 0, v15
	v_exp_f32_e32 v15, v70
	v_fma_f32 v65, v71, s9, -v124
	v_mul_f32_e32 v67, v11, v67
	v_cndmask_b32_e32 v146, 0, v66, vcc
	v_cmp_ne_u32_e32 vcc, 0, v142
	v_exp_f32_e32 v65, v65
	v_mul_f32_e32 v68, v11, v68
	v_cndmask_b32_e32 v142, 0, v67, vcc
	v_cmp_ne_u32_e32 vcc, 0, v143
	v_and_b32_e32 v14, 32, v12
	v_mul_f32_e32 v69, v11, v69
	v_cndmask_b32_e32 v13, 0, v68, vcc
	v_cmp_ne_u32_e32 vcc, 0, v14
	v_and_b32_e32 v64, 64, v12
	v_mul_f32_e32 v15, v11, v15
	v_cndmask_b32_e32 v14, 0, v69, vcc
	v_cmp_ne_u32_e32 vcc, 0, v64
	s_waitcnt lgkmcnt(1)
	v_mfma_f32_32x32x16_bf16 v[48:63], v[134:137], v[180:183], v[48:63]
	v_and_b32_e32 v67, 0x100, v12
	v_cndmask_b32_e32 v64, 0, v15, vcc
	v_mul_f32_e32 v15, v11, v65
	v_fma_f32 v65, v72, s9, -v124
	v_exp_f32_e32 v66, v65
	v_and_b32_e32 v65, 0x80, v12
	v_cmp_ne_u32_e32 vcc, 0, v65
	v_and_b32_e32 v68, 0x200, v12
	s_waitcnt lgkmcnt(0)
	v_mfma_f32_32x32x16_bf16 v[48:63], v[138:141], v[184:187], v[48:63]
	v_cndmask_b32_e32 v65, 0, v15, vcc
	v_mul_f32_e32 v15, v11, v66
	v_fma_f32 v66, v73, s9, -v124
	v_exp_f32_e32 v66, v66
	v_cmp_ne_u32_e32 vcc, 0, v67
	v_fma_f32 v67, v74, s9, -v124
	v_exp_f32_e32 v67, v67
	v_cndmask_b32_e32 v15, 0, v15, vcc
	v_cmp_ne_u32_e32 vcc, 0, v68
	v_fma_f32 v68, v75, s9, -v124
	v_exp_f32_e32 v69, v68
	v_mul_f32_e32 v66, v11, v66
	v_and_b32_e32 v68, 0x400, v12
	v_cndmask_b32_e32 v66, 0, v66, vcc
	v_mul_f32_e32 v67, v11, v67
	v_cmp_ne_u32_e32 vcc, 0, v68
	v_and_b32_e32 v71, 0x1000, v12
	v_and_b32_e32 v72, 0x2000, v12
	v_cndmask_b32_e32 v68, 0, v67, vcc
	v_mul_f32_e32 v67, v11, v69
	v_fma_f32 v69, v76, s9, -v124
	v_exp_f32_e32 v70, v69
	v_and_b32_e32 v69, 0x800, v12
	v_cmp_ne_u32_e32 vcc, 0, v69
	v_fma_f32 v48, v48, s9, -v124
	v_exp_f32_e32 v48, v48
	v_cndmask_b32_e32 v69, 0, v67, vcc
	v_mul_f32_e32 v67, v11, v70
	v_fma_f32 v70, v77, s9, -v124
	v_exp_f32_e32 v70, v70
	v_cmp_ne_u32_e32 vcc, 0, v71
	v_fma_f32 v71, v78, s9, -v124
	v_exp_f32_e32 v71, v71
	v_cndmask_b32_e32 v67, 0, v67, vcc
	v_cmp_ne_u32_e32 vcc, 0, v72
	v_fma_f32 v72, v79, s9, -v124
	v_exp_f32_e32 v72, v72
	v_mul_f32_e32 v70, v11, v70
	v_and_b32_e32 v73, 0x4000, v12
	v_cndmask_b32_e32 v70, 0, v70, vcc
	v_mul_f32_e32 v71, v11, v71
	v_cmp_ne_u32_e32 vcc, 0, v73
	v_and_b32_e32 v73, 0x8000, v12
	v_fma_f32 v49, v49, s9, -v124
	v_cndmask_b32_e32 v71, 0, v71, vcc
	v_mul_f32_e32 v72, v11, v72
	v_cmp_ne_u32_e32 vcc, 0, v73
	v_exp_f32_e32 v49, v49
	v_and_b32_e32 v73, 0x10000, v12
	v_fma_f32 v50, v50, s9, -v124
	v_add_u32_e32 v78, v125, v247
	v_cndmask_b32_e32 v72, 0, v72, vcc
	v_mul_f32_e32 v48, v11, v48
	v_cmp_ne_u32_e32 vcc, 0, v73
	v_exp_f32_e32 v50, v50
	v_and_b32_e32 v73, 0x20000, v12
	v_fma_f32 v51, v51, s9, -v124
	v_add_u32_e32 v79, 0x2000, v78
	v_add_u32_e32 v78, 0x3000, v78
	v_cndmask_b32_e32 v48, 0, v48, vcc
	v_cmp_ne_u32_e32 vcc, 0, v73
	v_exp_f32_e32 v73, v51
	v_cvt_pk_bf16_f32 v74, v144, v145
	v_cvt_pk_bf16_f32 v75, v146, v142
	v_cvt_pk_bf16_f32 v76, v13, v14
	v_cvt_pk_bf16_f32 v77, v64, v65
	s_nop 1
	ds_read2_b64 v[126:129], v79 offset0:128 offset1:130
	ds_read2_b64 v[130:133], v78 offset0:192 offset1:194
	v_mul_f32_e32 v49, v11, v49
	v_and_b32_e32 v51, 0x40000, v12
	v_cndmask_b32_e32 v49, 0, v49, vcc
	v_mul_f32_e32 v50, v11, v50
	v_cmp_ne_u32_e32 vcc, 0, v51
	v_fma_f32 v52, v52, s9, -v124
	v_fma_f32 v53, v53, s9, -v124
	v_cndmask_b32_e32 v51, 0, v50, vcc
	v_mul_f32_e32 v50, v11, v73
	v_exp_f32_e32 v73, v52
	v_and_b32_e32 v52, 0x80000, v12
	v_cmp_ne_u32_e32 vcc, 0, v52
	v_exp_f32_e32 v53, v53
	v_fma_f32 v54, v54, s9, -v124
	v_cndmask_b32_e32 v52, 0, v50, vcc
	v_mul_f32_e32 v50, v11, v73
	v_and_b32_e32 v73, 0x100000, v12
	v_cmp_ne_u32_e32 vcc, 0, v73
	v_exp_f32_e32 v54, v54
	v_and_b32_e32 v73, 0x200000, v12
	v_fma_f32 v55, v55, s9, -v124
	s_waitcnt lgkmcnt(1)
; DI float sum8(float v) {
;   v += __int_as_float(__builtin_amdgcn_update_dpp(0, __float_as_int(v), 0xB1, 0xF, 0xF, true));
;   v += __int_as_float(__builtin_amdgcn_update_dpp(0, __float_as_int(v), 0x4E, 0xF, 0xF, true));
;   v += __int_as_float(__builtin_amdgcn_update_dpp(0, __float_as_int(v), 0x141, 0xF, 0xF, true));
;   return v;
; }
; DI void nsa_item(int ws, PP p, char* shm, int item) {
;     ...
;       pv_tile(Vs, s, o, rl, hh);
; #pragma unroll
;       for (int kb = 0; kb < 2; ++kb)
; #pragma unroll
;         for (int q4 = 0; q4 < 4; ++q4) {
;           float mainv = s[kb][4 * q4] + s[kb][4 * q4 + 1] + s[kb][4 * q4 + 2] + 0.5f * s[kb][4 * q4 + 3];
;           float sp = 0.5f * s[kb][4 * q4 + 3];
;           mainv = sum8(mainv);
;           sp = sum8(sp);
;           if (r == 0) {
;             const int j = 16 * i + 8 * kb + 2 * q4 + hh;
;             impm[tokl * 132 + j] = mainv;
;             imps[tokl * 132 + j + 1] = sp;
;           }
;         }
	v_mfma_f32_32x32x16_bf16 v[16:31], v[126:129], v[74:77], v[16:31]
	v_cvt_pk_bf16_f32 v126, v15, v66
	v_cvt_pk_bf16_f32 v127, v68, v69
	v_cvt_pk_bf16_f32 v128, v67, v70
	v_cvt_pk_bf16_f32 v129, v71, v72
	s_nop 1
	v_cndmask_b32_e32 v50, 0, v50, vcc
	v_cmp_ne_u32_e32 vcc, 0, v73
	v_exp_f32_e32 v73, v55
	ds_read2_b64 v[134:137], v79 offset0:132 offset1:134
	v_mul_f32_e32 v53, v11, v53
	v_and_b32_e32 v55, 0x400000, v12
	s_waitcnt lgkmcnt(1)
	v_mfma_f32_32x32x16_bf16 v[32:47], v[130:133], v[74:77], v[32:47]
	ds_read2_b64 v[74:77], v78 offset0:196 offset1:198
	v_cndmask_b32_e32 v53, 0, v53, vcc
	v_mul_f32_e32 v54, v11, v54
	v_cmp_ne_u32_e32 vcc, 0, v55
	v_fma_f32 v56, v56, s9, -v124
	v_fma_f32 v57, v57, s9, -v124
	v_cndmask_b32_e32 v55, 0, v54, vcc
	v_mul_f32_e32 v54, v11, v73
	v_exp_f32_e32 v73, v56
	v_and_b32_e32 v56, 0x800000, v12
	v_exp_f32_e32 v57, v57
	v_fma_f32 v58, v58, s9, -v124
	v_cmp_ne_u32_e32 vcc, 0, v56
	v_exp_f32_e32 v58, v58
	v_fma_f32 v59, v59, s9, -v124
	v_cndmask_b32_e32 v56, 0, v54, vcc
	v_mul_f32_e32 v54, v11, v73
	v_and_b32_e32 v73, 0x1000000, v12
	v_exp_f32_e32 v59, v59
	v_fma_f32 v60, v60, s9, -v124
	v_cvt_pk_bf16_f32 v130, v48, v49
	v_cvt_pk_bf16_f32 v131, v51, v52
	v_cvt_pk_bf16_f32 v132, v50, v53
	v_cvt_pk_bf16_f32 v133, v55, v56
	s_nop 1
	s_waitcnt lgkmcnt(0)
	v_mfma_f32_32x32x16_bf16 v[32:47], v[74:77], v[126:129], v[32:47]
	ds_read2_b64 v[74:77], v78 offset0:200 offset1:202
	v_cmp_ne_u32_e32 vcc, 0, v73
	v_and_b32_e32 v73, 0x2000000, v12
	v_exp_f32_e32 v60, v60
	v_fma_f32 v61, v61, s9, -v124
	v_cndmask_b32_e32 v54, 0, v54, vcc
	v_mul_f32_e32 v57, v11, v57
	v_mfma_f32_32x32x16_bf16 v[16:31], v[134:137], v[126:129], v[16:31]
	ds_read2_b64 v[134:137], v79 offset0:136 offset1:138
	v_cmp_ne_u32_e32 vcc, 0, v73
	v_and_b32_e32 v73, 0x4000000, v12
	v_exp_f32_e32 v61, v61
	v_fma_f32 v62, v62, s9, -v124
	v_cndmask_b32_e32 v57, 0, v57, vcc
	v_mul_f32_e32 v58, v11, v58
	v_cmp_ne_u32_e32 vcc, 0, v73
	v_and_b32_e32 v73, 0x8000000, v12
	v_exp_f32_e32 v62, v62
	v_fma_f32 v63, v63, s9, -v124
	v_cndmask_b32_e32 v58, 0, v58, vcc
	v_mul_f32_e32 v59, v11, v59
	v_cmp_ne_u32_e32 vcc, 0, v73
	v_and_b32_e32 v73, 0x10000000, v12
	v_exp_f32_e32 v63, v63
	v_cndmask_b32_e32 v59, 0, v59, vcc
	v_mul_f32_e32 v60, v11, v60
	v_cmp_ne_u32_e32 vcc, 0, v73
	v_and_b32_e32 v73, 0x20000000, v12
	v_mul_f32_e32 v61, v11, v61
	v_cndmask_b32_e32 v60, 0, v60, vcc
	v_cmp_ne_u32_e32 vcc, 0, v73
	v_and_b32_e32 v73, 2.0, v12
	v_mul_f32_e32 v62, v11, v62
	v_cndmask_b32_e32 v61, 0, v61, vcc
	v_cmp_ne_u32_e32 vcc, 0, v73
	v_mul_f32_e32 v63, v11, v63
	s_waitcnt lgkmcnt(1)
	v_mfma_f32_32x32x16_bf16 v[32:47], v[74:77], v[130:133], v[32:47]
	v_cndmask_b32_e32 v62, 0, v62, vcc
	v_cmp_gt_i32_e32 vcc, 0, v12
	s_nop 1
	v_cndmask_b32_e32 v12, 0, v63, vcc
	v_cvt_pk_bf16_f32 v74, v54, v57
	v_cvt_pk_bf16_f32 v75, v58, v59
	v_cvt_pk_bf16_f32 v76, v60, v61
	v_cvt_pk_bf16_f32 v77, v62, v12
	s_nop 1
	ds_read2_b64 v[126:129], v79 offset0:140 offset1:142
	s_waitcnt lgkmcnt(1)
	v_mfma_f32_32x32x16_bf16 v[16:31], v[134:137], v[130:133], v[16:31]
	v_add_f32_e32 v63, v144, v145
	v_add_f32_e32 v63, v146, v63
	v_fmac_f32_e32 v63, 0.5, v142
	s_nop 1
	v_add_f32_dpp v63, v63, v63 quad_perm:[1,0,3,2] row_mask:0xf bank_mask:0xf bound_ctrl:1
	s_waitcnt lgkmcnt(0)
	v_mfma_f32_32x32x16_bf16 v[16:31], v[126:129], v[74:77], v[16:31]
	ds_read2_b64 v[126:129], v78 offset0:204 offset1:206
	v_add_f32_dpp v73, v63, v63 quad_perm:[2,3,0,1] row_mask:0xf bank_mask:0xf bound_ctrl:1
	s_waitcnt lgkmcnt(0)
	v_mfma_f32_32x32x16_bf16 v[32:47], v[126:129], v[74:77], v[32:47]
	v_mul_f32_e32 v75, 0.5, v142
	v_mov_b32_dpp v74, v73 row_half_mirror row_mask:0xf bank_mask:0xf bound_ctrl:1
	s_nop 0
	v_mov_b32_dpp v63, v75 quad_perm:[1,0,3,2] row_mask:0xf bank_mask:0xf bound_ctrl:1
	v_fmac_f32_e32 v63, 0.5, v142
	s_nop 1
	v_add_f32_dpp v75, v63, v63 quad_perm:[2,3,0,1] row_mask:0xf bank_mask:0xf bound_ctrl:1
	v_add_u32_e32 v63, s5, v10
	s_nop 0
	v_mov_b32_dpp v76, v75 row_half_mirror row_mask:0xf bank_mask:0xf bound_ctrl:1
	s_and_saveexec_b64 s[14:15], s[10:11]
	s_cbranch_execz .LBB0_1612
	v_add_f32_e32 v73, v73, v74
	v_add_f32_e32 v75, v75, v76
	ds_write_b32 v63, v73
	ds_write_b32 v63, v75 offset:16900
